# norm phases: residual-row pieces loaded together instead of load+wait per piece (layer-1 norm1, layer-0 norm2); ctx split-K partials batched per piece
# speedup vs baseline: 1.0064x; 1.0064x over previous
; __device__ __forceinline__ void phase_norm_mod(const float* srcL, const float* srcC, const float* g, const float* mod_sh, const float* mod_sc, bf16_t* dst, int nrows, const float* part = nullptr, const float* pgate = nullptr, const bf16_t* srcLb = nullptr) {
;     ...
;         const bool isc = row >= NLAT; const float* src = isc ? srcC + (size_t)(row - NLAT) * DM : srcL + (size_t)row * DM; const int ridx = isc ? 4 : (row >> 12);
;         f32x4 v[8]; float s = 0.f;
; #pragma unroll
;         for (int j = 0; j < 8; ++j) {
;             if (srcLb != nullptr && !isc) { const unsigned long long w = *(const unsigned long long*)(srcLb + (size_t)row * DM + j * 256 + lane * 4); const unsigned lo = (unsigned)w, hi = (unsigned)(w >> 32);
;                 v[j] = (f32x4){__uint_as_float(lo << 16), __uint_as_float(lo & 0xffff0000u), __uint_as_float(hi << 16), __uint_as_float(hi & 0xffff0000u)}; }
;             else if (srcLb == nullptr && !isc) v[j] = __builtin_nontemporal_load((const f32x4*)(src + j * 256 + lane * 4));
;             else v[j] = *(const f32x4*)(src + j * 256 + lane * 4);
.LBB0_1153:
	s_movk_i32 s6, 0x4000
	v_cmp_gt_i32_e64 s[38:39], s6, v32
	s_movk_i32 s6, 0x3fff
	v_cmp_lt_i32_e32 vcc, s6, v32
	v_mov_b64_e32 v[0:1], v[32:33]
	v_mov_b64_e32 v[2:3], v[50:51]
	s_and_saveexec_b64 s[8:9], vcc
	v_add_u32_e32 v0, 0xffffc000, v32
	v_mov_b32_e32 v1, v35
	v_lshlrev_b64 v[0:1], 13, v[0:1]
	v_lshl_add_u64 v[2:3], s[4:5], 0, v[0:1]
	v_mov_b32_e32 v0, v32
	v_mov_b32_e32 v1, v35
	s_or_b64 exec, exec, s[8:9]
	v_lshlrev_b64 v[66:67], 12, v[0:1]
	v_lshl_add_u64 v[0:1], v[36:37], 0, v[66:67]
	s_and_saveexec_b64 s[6:7], s[38:39]
	s_xor_b64 s[8:9], exec, s[6:7]
	s_cbranch_execz .LBB0_1157
	global_load_dwordx2 v[102:103], v[0:1], off
	global_load_dwordx2 v[104:105], v[0:1], off offset:512
	global_load_dwordx2 v[106:107], v[0:1], off offset:1024
	global_load_dwordx2 v[108:109], v[0:1], off offset:1536
	global_load_dwordx2 v[110:111], v[0:1], off offset:2048
	global_load_dwordx2 v[112:113], v[0:1], off offset:2560
	global_load_dwordx2 v[114:115], v[0:1], off offset:3072
	global_load_dwordx2 v[116:117], v[0:1], off offset:3584
	s_waitcnt vmcnt(0)
	v_mov_b32_e32 v4, v102
	v_mov_b32_e32 v5, v103
	v_lshlrev_b32_e32 v24, 16, v4
	v_and_b32_e32 v25, 0xffff0000, v4
	v_lshlrev_b32_e32 v26, 16, v5
	v_and_b32_e32 v27, 0xffff0000, v5
	s_or_saveexec_b64 s[8:9], s[8:9]
	v_lshl_add_u64 v[60:61], v[2:3], 0, v[34:35]
	s_xor_b64 exec, exec, s[8:9]
	s_cbranch_execz .LBB0_1159
	s_branch .LBB0_1158

; __device__ __forceinline__ void phase_norm_mod(const float* srcL, const float* srcC, const float* g, const float* mod_sh, const float* mod_sc, bf16_t* dst, int nrows, const float* part = nullptr, const float* pgate = nullptr, const bf16_t* srcLb = nullptr) {
;     ...
;             if (srcLb != nullptr && !isc) { const unsigned long long w = *(const unsigned long long*)(srcLb + (size_t)row * DM + j * 256 + lane * 4); const unsigned lo = (unsigned)w, hi = (unsigned)(w >> 32);
;                 v[j] = (f32x4){__uint_as_float(lo << 16), __uint_as_float(lo & 0xffff0000u), __uint_as_float(hi << 16), __uint_as_float(hi & 0xffff0000u)}; }
.LBB0_1159:
	s_or_b64 exec, exec, s[8:9]
	s_and_saveexec_b64 s[6:7], s[38:39]
	s_xor_b64 s[8:9], exec, s[6:7]
	s_cbranch_execz .LBB0_1161
	v_mov_b32_e32 v2, v104
	v_mov_b32_e32 v3, v105
	v_lshlrev_b32_e32 v28, 16, v2
	v_and_b32_e32 v29, 0xffff0000, v2
	v_lshlrev_b32_e32 v30, 16, v3
	v_and_b32_e32 v31, 0xffff0000, v3
	s_andn2_saveexec_b64 s[8:9], s[8:9]
	s_cbranch_execz .LBB0_1163
	s_branch .LBB0_1162

; __device__ __forceinline__ void phase_norm_mod(const float* srcL, const float* srcC, const float* g, const float* mod_sh, const float* mod_sc, bf16_t* dst, int nrows, const float* part = nullptr, const float* pgate = nullptr, const bf16_t* srcLb = nullptr) {
;     ...
;             if (srcLb != nullptr && !isc) { const unsigned long long w = *(const unsigned long long*)(srcLb + (size_t)row * DM + j * 256 + lane * 4); const unsigned lo = (unsigned)w, hi = (unsigned)(w >> 32);
;                 v[j] = (f32x4){__uint_as_float(lo << 16), __uint_as_float(lo & 0xffff0000u), __uint_as_float(hi << 16), __uint_as_float(hi & 0xffff0000u)}; }
.LBB0_1163:
	s_or_b64 exec, exec, s[8:9]
	s_and_saveexec_b64 s[6:7], s[38:39]
	s_xor_b64 s[8:9], exec, s[6:7]
	s_cbranch_execz .LBB0_1165
	v_mov_b32_e32 v2, v106
	v_mov_b32_e32 v3, v107
	v_lshlrev_b32_e32 v20, 16, v2
	v_and_b32_e32 v21, 0xffff0000, v2
	v_lshlrev_b32_e32 v22, 16, v3
	v_and_b32_e32 v23, 0xffff0000, v3
	s_andn2_saveexec_b64 s[8:9], s[8:9]
	s_cbranch_execz .LBB0_1167
	s_branch .LBB0_1166

; __device__ __forceinline__ void phase_norm_mod(const float* srcL, const float* srcC, const float* g, const float* mod_sh, const float* mod_sc, bf16_t* dst, int nrows, const float* part = nullptr, const float* pgate = nullptr, const bf16_t* srcLb = nullptr) {
;     ...
;             if (srcLb != nullptr && !isc) { const unsigned long long w = *(const unsigned long long*)(srcLb + (size_t)row * DM + j * 256 + lane * 4); const unsigned lo = (unsigned)w, hi = (unsigned)(w >> 32);
;                 v[j] = (f32x4){__uint_as_float(lo << 16), __uint_as_float(lo & 0xffff0000u), __uint_as_float(hi << 16), __uint_as_float(hi & 0xffff0000u)}; }
.LBB0_1167:
	s_or_b64 exec, exec, s[8:9]
	s_and_saveexec_b64 s[6:7], s[38:39]
	s_xor_b64 s[8:9], exec, s[6:7]
	s_cbranch_execz .LBB0_1169
	v_mov_b32_e32 v2, v108
	v_mov_b32_e32 v3, v109
	v_lshlrev_b32_e32 v16, 16, v2
	v_and_b32_e32 v17, 0xffff0000, v2
	v_lshlrev_b32_e32 v18, 16, v3
	v_and_b32_e32 v19, 0xffff0000, v3
	s_andn2_saveexec_b64 s[8:9], s[8:9]
	s_cbranch_execz .LBB0_1171
	s_branch .LBB0_1170

; __device__ __forceinline__ void phase_norm_mod(const float* srcL, const float* srcC, const float* g, const float* mod_sh, const float* mod_sc, bf16_t* dst, int nrows, const float* part = nullptr, const float* pgate = nullptr, const bf16_t* srcLb = nullptr) {
;     ...
;             if (srcLb != nullptr && !isc) { const unsigned long long w = *(const unsigned long long*)(srcLb + (size_t)row * DM + j * 256 + lane * 4); const unsigned lo = (unsigned)w, hi = (unsigned)(w >> 32);
;                 v[j] = (f32x4){__uint_as_float(lo << 16), __uint_as_float(lo & 0xffff0000u), __uint_as_float(hi << 16), __uint_as_float(hi & 0xffff0000u)}; }
.LBB0_1171:
	s_or_b64 exec, exec, s[8:9]
	s_and_saveexec_b64 s[6:7], s[38:39]
	s_xor_b64 s[8:9], exec, s[6:7]
	s_cbranch_execz .LBB0_1173
	v_mov_b32_e32 v2, v110
	v_mov_b32_e32 v3, v111
	v_lshlrev_b32_e32 v12, 16, v2
	v_and_b32_e32 v13, 0xffff0000, v2
	v_lshlrev_b32_e32 v14, 16, v3
	v_and_b32_e32 v15, 0xffff0000, v3
	s_andn2_saveexec_b64 s[8:9], s[8:9]
	s_cbranch_execz .LBB0_1175
	s_branch .LBB0_1174

; __device__ __forceinline__ void phase_norm_mod(const float* srcL, const float* srcC, const float* g, const float* mod_sh, const float* mod_sc, bf16_t* dst, int nrows, const float* part = nullptr, const float* pgate = nullptr, const bf16_t* srcLb = nullptr) {
;     ...
;             if (srcLb != nullptr && !isc) { const unsigned long long w = *(const unsigned long long*)(srcLb + (size_t)row * DM + j * 256 + lane * 4); const unsigned lo = (unsigned)w, hi = (unsigned)(w >> 32);
;                 v[j] = (f32x4){__uint_as_float(lo << 16), __uint_as_float(lo & 0xffff0000u), __uint_as_float(hi << 16), __uint_as_float(hi & 0xffff0000u)}; }
.LBB0_1175:
	s_or_b64 exec, exec, s[8:9]
	s_and_saveexec_b64 s[6:7], s[38:39]
	s_xor_b64 s[8:9], exec, s[6:7]
	s_cbranch_execz .LBB0_1177
	v_mov_b32_e32 v2, v112
	v_mov_b32_e32 v3, v113
	v_lshlrev_b32_e32 v8, 16, v2
	v_and_b32_e32 v9, 0xffff0000, v2
	v_lshlrev_b32_e32 v10, 16, v3
	v_and_b32_e32 v11, 0xffff0000, v3
	s_andn2_saveexec_b64 s[8:9], s[8:9]
	s_cbranch_execz .LBB0_1179
	s_branch .LBB0_1178

; __device__ __forceinline__ void phase_norm_mod(const float* srcL, const float* srcC, const float* g, const float* mod_sh, const float* mod_sc, bf16_t* dst, int nrows, const float* part = nullptr, const float* pgate = nullptr, const bf16_t* srcLb = nullptr) {
;     ...
;             if (srcLb != nullptr && !isc) { const unsigned long long w = *(const unsigned long long*)(srcLb + (size_t)row * DM + j * 256 + lane * 4); const unsigned lo = (unsigned)w, hi = (unsigned)(w >> 32);
;                 v[j] = (f32x4){__uint_as_float(lo << 16), __uint_as_float(lo & 0xffff0000u), __uint_as_float(hi << 16), __uint_as_float(hi & 0xffff0000u)}; }
.LBB0_1179:
	s_or_b64 exec, exec, s[8:9]
	s_and_saveexec_b64 s[6:7], s[38:39]
	s_xor_b64 s[8:9], exec, s[6:7]
	s_cbranch_execz .LBB0_1181
	v_mov_b32_e32 v2, v114
	v_mov_b32_e32 v3, v115
	v_lshlrev_b32_e32 v4, 16, v2
	v_and_b32_e32 v5, 0xffff0000, v2
	v_lshlrev_b32_e32 v6, 16, v3
	v_and_b32_e32 v7, 0xffff0000, v3
	s_andn2_saveexec_b64 s[8:9], s[8:9]
	s_cbranch_execz .LBB0_1183
	s_branch .LBB0_1182

; __device__ __forceinline__ void phase_norm_mod(const float* srcL, const float* srcC, const float* g, const float* mod_sh, const float* mod_sc, bf16_t* dst, int nrows, const float* part = nullptr, const float* pgate = nullptr, const bf16_t* srcLb = nullptr) {
;     ...
;             if (srcLb != nullptr && !isc) { const unsigned long long w = *(const unsigned long long*)(srcLb + (size_t)row * DM + j * 256 + lane * 4); const unsigned lo = (unsigned)w, hi = (unsigned)(w >> 32);
;                 v[j] = (f32x4){__uint_as_float(lo << 16), __uint_as_float(lo & 0xffff0000u), __uint_as_float(hi << 16), __uint_as_float(hi & 0xffff0000u)}; }
.LBB0_1183:
	s_or_b64 exec, exec, s[8:9]
	s_and_saveexec_b64 s[6:7], s[38:39]
	s_xor_b64 s[8:9], exec, s[6:7]
	s_cbranch_execz .LBB0_1185
	v_mov_b32_e32 v2, v116
	v_mov_b32_e32 v3, v117
	v_lshlrev_b32_e32 v0, 16, v2
	v_and_b32_e32 v1, 0xffff0000, v2
	v_lshlrev_b32_e32 v2, 16, v3
	v_and_b32_e32 v3, 0xffff0000, v3
	s_andn2_saveexec_b64 s[8:9], s[8:9]
	s_cbranch_execz .LBB0_1152
	s_branch .LBB0_1186

; __device__ __forceinline__ void phase_norm_mod(const float* srcL, const float* srcC, const float* g, const float* mod_sh, const float* mod_sc, bf16_t* dst, int nrows, const float* part = nullptr, const float* pgate = nullptr, const bf16_t* srcLb = nullptr) {
;     ...
;         const bool isc = row >= NLAT; const float* src = isc ? srcC + (size_t)(row - NLAT) * DM : srcL + (size_t)row * DM; const int ridx = isc ? 4 : (row >> 12);
;         f32x4 v[8]; float s = 0.f;
; #pragma unroll
;         for (int j = 0; j < 8; ++j) {
;             if (srcLb != nullptr && !isc) { const unsigned long long w = *(const unsigned long long*)(srcLb + (size_t)row * DM + j * 256 + lane * 4); const unsigned lo = (unsigned)w, hi = (unsigned)(w >> 32);
;                 v[j] = (f32x4){__uint_as_float(lo << 16), __uint_as_float(lo & 0xffff0000u), __uint_as_float(hi << 16), __uint_as_float(hi & 0xffff0000u)}; }
.LBB0_1469:
	s_movk_i32 s8, 0x3fff
	v_cmp_lt_i32_e64 s[38:39], s8, v32
	s_movk_i32 s8, 0x4000
	v_mov_b32_e32 v36, v32
	v_cmp_gt_i32_e64 s[40:41], s8, v32
	v_add_u32_e32 v4, 0xffffc000, v32
	v_mov_b64_e32 v[0:1], v[36:37]
	s_and_saveexec_b64 s[8:9], s[40:41]
	s_xor_b64 s[8:9], exec, s[8:9]
	v_mov_b32_e32 v5, v37
	v_mov_b64_e32 v[0:1], v[32:33]
	s_or_saveexec_b64 s[8:9], s[8:9]
	v_mov_b64_e32 v[6:7], v[62:63]
	s_xor_b64 exec, exec, s[8:9]
	v_mov_b32_e32 v5, v37
	v_lshlrev_b64 v[2:3], 13, v[4:5]
	v_lshl_add_u64 v[6:7], s[4:5], 0, v[2:3]
	s_or_b64 exec, exec, s[8:9]
	v_lshlrev_b64 v[74:75], 12, v[0:1]
	v_lshl_add_u64 v[78:79], v[38:39], 0, v[74:75]
	s_and_saveexec_b64 s[8:9], s[40:41]
	s_xor_b64 s[8:9], exec, s[8:9]
	s_cbranch_execz .LBB0_1475
	global_load_dwordx2 v[102:103], v[78:79], off
	global_load_dwordx2 v[104:105], v[78:79], off offset:512
	global_load_dwordx2 v[106:107], v[78:79], off offset:1024
	global_load_dwordx2 v[108:109], v[78:79], off offset:1536
	global_load_dwordx2 v[110:111], v[78:79], off offset:2048
	global_load_dwordx2 v[112:113], v[78:79], off offset:2560
	global_load_dwordx2 v[114:115], v[78:79], off offset:3072
	global_load_dwordx2 v[116:117], v[78:79], off offset:3584
	s_waitcnt vmcnt(0)
	v_mov_b32_e32 v2, v102
	v_mov_b32_e32 v3, v103
	v_lshlrev_b32_e32 v0, 16, v2
	v_and_b32_e32 v1, 0xffff0000, v2
	v_lshlrev_b32_e32 v2, 16, v3
	v_and_b32_e32 v3, 0xffff0000, v3

; __device__ __forceinline__ void phase_norm_mod(const float* srcL, const float* srcC, const float* g, const float* mod_sh, const float* mod_sc, bf16_t* dst, int nrows, const float* part = nullptr, const float* pgate = nullptr, const bf16_t* srcLb = nullptr) {
;     ...
;             if (part != nullptr && isc) { const size_t po = (size_t)(row - NLAT) * DM + j * 256 + lane * 4; f32x4 ps = *(const f32x4*)(part + po);
; #pragma unroll
;                 for (int p = 1; p < 8; ++p) ps = ps + *(const f32x4*)(part + (size_t)p * (1024 * 2048) + po);
;                 v[j] = v[j] + ps * *(const f32x4*)(pgate + 4 * 12288 + j * 256 + lane * 4); }
.LBB0_1477:
	s_or_b64 exec, exec, s[8:9]
	v_lshlrev_b64 v[4:5], 11, v[4:5]
	v_or_b32_e32 v4, v4, v34
	v_lshl_add_u64 v[76:77], v[4:5], 2, s[44:45]
	s_and_saveexec_b64 s[8:9], s[38:39]
	s_cbranch_execz .LBB0_1479
	global_load_dwordx4 v[166:169], v[76:77], off
	v_add_co_u32_e32 v152, vcc, s1, v76
	s_nop 1
	v_addc_co_u32_e32 v153, vcc, 0, v77, vcc
	global_load_dwordx4 v[170:173], v[152:153], off
	v_add_co_u32_e32 v154, vcc, s6, v76
	s_nop 1
	v_addc_co_u32_e32 v155, vcc, 0, v77, vcc
	global_load_dwordx4 v[174:177], v[154:155], off
	v_add_co_u32_e32 v156, vcc, s7, v76
	s_nop 1
	v_addc_co_u32_e32 v157, vcc, 0, v77, vcc
	global_load_dwordx4 v[178:181], v[156:157], off
	v_add_co_u32_e32 v158, vcc, s10, v76
	s_nop 1
	v_addc_co_u32_e32 v159, vcc, 0, v77, vcc
	global_load_dwordx4 v[182:185], v[158:159], off
	v_add_co_u32_e32 v160, vcc, s11, v76
	s_nop 1
	v_addc_co_u32_e32 v161, vcc, 0, v77, vcc
	global_load_dwordx4 v[186:189], v[160:161], off
	v_add_co_u32_e32 v162, vcc, s14, v76
	s_nop 1
	v_addc_co_u32_e32 v163, vcc, 0, v77, vcc
	global_load_dwordx4 v[190:193], v[162:163], off
	v_add_co_u32_e32 v164, vcc, s15, v76
	s_nop 1
	v_addc_co_u32_e32 v165, vcc, 0, v77, vcc
	global_load_dwordx4 v[194:197], v[164:165], off
	s_waitcnt vmcnt(0)
	v_pk_add_f32 v[8:9], v[166:167], v[170:171]
	v_pk_add_f32 v[10:11], v[168:169], v[172:173]
	v_pk_add_f32 v[8:9], v[8:9], v[174:175]
	v_pk_add_f32 v[10:11], v[10:11], v[176:177]
	v_pk_add_f32 v[8:9], v[8:9], v[178:179]
	v_pk_add_f32 v[10:11], v[10:11], v[180:181]
	v_pk_add_f32 v[8:9], v[8:9], v[182:183]
	v_pk_add_f32 v[10:11], v[10:11], v[184:185]
	v_pk_add_f32 v[8:9], v[8:9], v[186:187]
	v_pk_add_f32 v[10:11], v[10:11], v[188:189]
	v_pk_add_f32 v[8:9], v[8:9], v[190:191]
	v_pk_add_f32 v[10:11], v[10:11], v[192:193]
	v_pk_add_f32 v[10:11], v[10:11], v[196:197]
	v_pk_add_f32 v[8:9], v[8:9], v[194:195]
	global_load_dwordx4 v[4:7], v[40:41], off
	s_waitcnt vmcnt(0)
	v_pk_fma_f32 v[2:3], v[10:11], v[6:7], v[2:3]
	v_pk_fma_f32 v[0:1], v[8:9], v[4:5], v[0:1]
.LBB0_1479:
	s_or_b64 exec, exec, s[8:9]
	s_and_saveexec_b64 s[8:9], s[40:41]
	s_xor_b64 s[8:9], exec, s[8:9]
	s_cbranch_execz .LBB0_1506
	v_mov_b32_e32 v6, v104
	v_mov_b32_e32 v7, v105
	v_lshlrev_b32_e32 v4, 16, v6
	v_and_b32_e32 v5, 0xffff0000, v6
	v_lshlrev_b32_e32 v6, 16, v7
	v_and_b32_e32 v7, 0xffff0000, v7
	s_andn2_saveexec_b64 s[8:9], s[8:9]
	s_cbranch_execnz .LBB0_1507

; __device__ __forceinline__ void phase_norm_mod(const float* srcL, const float* srcC, const float* g, const float* mod_sh, const float* mod_sc, bf16_t* dst, int nrows, const float* part = nullptr, const float* pgate = nullptr, const bf16_t* srcLb = nullptr) {
;     ...
;             if (srcLb != nullptr && !isc) { const unsigned long long w = *(const unsigned long long*)(srcLb + (size_t)row * DM + j * 256 + lane * 4); const unsigned lo = (unsigned)w, hi = (unsigned)(w >> 32);
;                 v[j] = (f32x4){__uint_as_float(lo << 16), __uint_as_float(lo & 0xffff0000u), __uint_as_float(hi << 16), __uint_as_float(hi & 0xffff0000u)}; }
;             else if (srcLb == nullptr && !isc) v[j] = __builtin_nontemporal_load((const f32x4*)(src + j * 256 + lane * 4));
;             else v[j] = *(const f32x4*)(src + j * 256 + lane * 4);
;             if (part != nullptr && isc) { const size_t po = (size_t)(row - NLAT) * DM + j * 256 + lane * 4; f32x4 ps = *(const f32x4*)(part + po);
; #pragma unroll
;                 for (int p = 1; p < 8; ++p) ps = ps + *(const f32x4*)(part + (size_t)p * (1024 * 2048) + po);
;                 v[j] = v[j] + ps * *(const f32x4*)(pgate + 4 * 12288 + j * 256 + lane * 4); }
.LBB0_1482:
	global_load_dwordx4 v[166:169], v[76:77], off offset:1024
	v_add_co_u32_e32 v152, vcc, s1, v76
	s_nop 1
	v_addc_co_u32_e32 v153, vcc, 0, v77, vcc
	global_load_dwordx4 v[170:173], v[152:153], off offset:1024
	v_add_co_u32_e32 v154, vcc, s6, v76
	s_nop 1
	v_addc_co_u32_e32 v155, vcc, 0, v77, vcc
	global_load_dwordx4 v[174:177], v[154:155], off offset:1024
	v_add_co_u32_e32 v156, vcc, s7, v76
	s_nop 1
	v_addc_co_u32_e32 v157, vcc, 0, v77, vcc
	global_load_dwordx4 v[178:181], v[156:157], off offset:1024
	v_add_co_u32_e32 v158, vcc, s10, v76
	s_nop 1
	v_addc_co_u32_e32 v159, vcc, 0, v77, vcc
	global_load_dwordx4 v[182:185], v[158:159], off offset:1024
	v_add_co_u32_e32 v160, vcc, s11, v76
	s_nop 1
	v_addc_co_u32_e32 v161, vcc, 0, v77, vcc
	global_load_dwordx4 v[186:189], v[160:161], off offset:1024
	v_add_co_u32_e32 v162, vcc, s14, v76
	s_nop 1
	v_addc_co_u32_e32 v163, vcc, 0, v77, vcc
	global_load_dwordx4 v[190:193], v[162:163], off offset:1024
	v_add_co_u32_e32 v164, vcc, s15, v76
	s_nop 1
	v_addc_co_u32_e32 v165, vcc, 0, v77, vcc
	global_load_dwordx4 v[194:197], v[164:165], off offset:1024
	s_waitcnt vmcnt(0)
	v_pk_add_f32 v[12:13], v[166:167], v[170:171]
	v_pk_add_f32 v[14:15], v[168:169], v[172:173]
	v_pk_add_f32 v[12:13], v[12:13], v[174:175]
	v_pk_add_f32 v[14:15], v[14:15], v[176:177]
	v_pk_add_f32 v[12:13], v[12:13], v[178:179]
	v_pk_add_f32 v[14:15], v[14:15], v[180:181]
	v_pk_add_f32 v[12:13], v[12:13], v[182:183]
	v_pk_add_f32 v[14:15], v[14:15], v[184:185]
	v_pk_add_f32 v[12:13], v[12:13], v[186:187]
	v_pk_add_f32 v[14:15], v[14:15], v[188:189]
	v_pk_add_f32 v[12:13], v[12:13], v[190:191]
	v_pk_add_f32 v[14:15], v[14:15], v[192:193]
	v_pk_add_f32 v[14:15], v[14:15], v[196:197]
	v_pk_add_f32 v[12:13], v[12:13], v[194:195]
	global_load_dwordx4 v[8:11], v[40:41], off offset:1024
	s_waitcnt vmcnt(0)
	v_pk_fma_f32 v[6:7], v[14:15], v[10:11], v[6:7]
	v_pk_fma_f32 v[4:5], v[12:13], v[8:9], v[4:5]
.LBB0_1483:
	s_or_b64 exec, exec, s[8:9]
	s_and_saveexec_b64 s[8:9], s[40:41]
	s_xor_b64 s[8:9], exec, s[8:9]
	s_cbranch_execz .LBB0_1508
	v_mov_b32_e32 v10, v106
	v_mov_b32_e32 v11, v107
	v_lshlrev_b32_e32 v8, 16, v10
	v_and_b32_e32 v9, 0xffff0000, v10
	v_lshlrev_b32_e32 v10, 16, v11
	v_and_b32_e32 v11, 0xffff0000, v11
	s_andn2_saveexec_b64 s[8:9], s[8:9]
	s_cbranch_execnz .LBB0_1509

; __device__ __forceinline__ void phase_norm_mod(const float* srcL, const float* srcC, const float* g, const float* mod_sh, const float* mod_sc, bf16_t* dst, int nrows, const float* part = nullptr, const float* pgate = nullptr, const bf16_t* srcLb = nullptr) {
;     ...
;             if (srcLb != nullptr && !isc) { const unsigned long long w = *(const unsigned long long*)(srcLb + (size_t)row * DM + j * 256 + lane * 4); const unsigned lo = (unsigned)w, hi = (unsigned)(w >> 32);
;                 v[j] = (f32x4){__uint_as_float(lo << 16), __uint_as_float(lo & 0xffff0000u), __uint_as_float(hi << 16), __uint_as_float(hi & 0xffff0000u)}; }
;             else if (srcLb == nullptr && !isc) v[j] = __builtin_nontemporal_load((const f32x4*)(src + j * 256 + lane * 4));
;             else v[j] = *(const f32x4*)(src + j * 256 + lane * 4);
;             if (part != nullptr && isc) { const size_t po = (size_t)(row - NLAT) * DM + j * 256 + lane * 4; f32x4 ps = *(const f32x4*)(part + po);
; #pragma unroll
;                 for (int p = 1; p < 8; ++p) ps = ps + *(const f32x4*)(part + (size_t)p * (1024 * 2048) + po);
;                 v[j] = v[j] + ps * *(const f32x4*)(pgate + 4 * 12288 + j * 256 + lane * 4); }
.LBB0_1486:
	global_load_dwordx4 v[166:169], v[76:77], off offset:2048
	v_add_co_u32_e32 v152, vcc, s1, v76
	s_nop 1
	v_addc_co_u32_e32 v153, vcc, 0, v77, vcc
	global_load_dwordx4 v[170:173], v[152:153], off offset:2048
	v_add_co_u32_e32 v154, vcc, s6, v76
	s_nop 1
	v_addc_co_u32_e32 v155, vcc, 0, v77, vcc
	global_load_dwordx4 v[174:177], v[154:155], off offset:2048
	v_add_co_u32_e32 v156, vcc, s7, v76
	s_nop 1
	v_addc_co_u32_e32 v157, vcc, 0, v77, vcc
	global_load_dwordx4 v[178:181], v[156:157], off offset:2048
	v_add_co_u32_e32 v158, vcc, s10, v76
	s_nop 1
	v_addc_co_u32_e32 v159, vcc, 0, v77, vcc
	global_load_dwordx4 v[182:185], v[158:159], off offset:2048
	v_add_co_u32_e32 v160, vcc, s11, v76
	s_nop 1
	v_addc_co_u32_e32 v161, vcc, 0, v77, vcc
	global_load_dwordx4 v[186:189], v[160:161], off offset:2048
	v_add_co_u32_e32 v162, vcc, s14, v76
	s_nop 1
	v_addc_co_u32_e32 v163, vcc, 0, v77, vcc
	global_load_dwordx4 v[190:193], v[162:163], off offset:2048
	v_add_co_u32_e32 v164, vcc, s15, v76
	s_nop 1
	v_addc_co_u32_e32 v165, vcc, 0, v77, vcc
	global_load_dwordx4 v[194:197], v[164:165], off offset:2048
	s_waitcnt vmcnt(0)
	v_pk_add_f32 v[16:17], v[166:167], v[170:171]
	v_pk_add_f32 v[18:19], v[168:169], v[172:173]
	v_pk_add_f32 v[16:17], v[16:17], v[174:175]
	v_pk_add_f32 v[18:19], v[18:19], v[176:177]
	v_pk_add_f32 v[16:17], v[16:17], v[178:179]
	v_pk_add_f32 v[18:19], v[18:19], v[180:181]
	v_pk_add_f32 v[16:17], v[16:17], v[182:183]
	v_pk_add_f32 v[18:19], v[18:19], v[184:185]
	v_pk_add_f32 v[16:17], v[16:17], v[186:187]
	v_pk_add_f32 v[18:19], v[18:19], v[188:189]
	v_pk_add_f32 v[16:17], v[16:17], v[190:191]
	v_pk_add_f32 v[18:19], v[18:19], v[192:193]
	v_pk_add_f32 v[18:19], v[18:19], v[196:197]
	v_pk_add_f32 v[16:17], v[16:17], v[194:195]
	global_load_dwordx4 v[12:15], v[40:41], off offset:2048
	s_waitcnt vmcnt(0)
	v_pk_fma_f32 v[10:11], v[18:19], v[14:15], v[10:11]
	v_pk_fma_f32 v[8:9], v[16:17], v[12:13], v[8:9]
.LBB0_1487:
	s_or_b64 exec, exec, s[8:9]
	s_and_saveexec_b64 s[8:9], s[40:41]
	s_xor_b64 s[8:9], exec, s[8:9]
	s_cbranch_execz .LBB0_1510
	v_mov_b32_e32 v14, v108
	v_mov_b32_e32 v15, v109
	v_lshlrev_b32_e32 v12, 16, v14
	v_and_b32_e32 v13, 0xffff0000, v14
	v_lshlrev_b32_e32 v14, 16, v15
	v_and_b32_e32 v15, 0xffff0000, v15
	s_andn2_saveexec_b64 s[8:9], s[8:9]
	s_cbranch_execnz .LBB0_1511

; __device__ __forceinline__ void phase_norm_mod(const float* srcL, const float* srcC, const float* g, const float* mod_sh, const float* mod_sc, bf16_t* dst, int nrows, const float* part = nullptr, const float* pgate = nullptr, const bf16_t* srcLb = nullptr) {
;     ...
;             if (srcLb != nullptr && !isc) { const unsigned long long w = *(const unsigned long long*)(srcLb + (size_t)row * DM + j * 256 + lane * 4); const unsigned lo = (unsigned)w, hi = (unsigned)(w >> 32);
;                 v[j] = (f32x4){__uint_as_float(lo << 16), __uint_as_float(lo & 0xffff0000u), __uint_as_float(hi << 16), __uint_as_float(hi & 0xffff0000u)}; }
;             else if (srcLb == nullptr && !isc) v[j] = __builtin_nontemporal_load((const f32x4*)(src + j * 256 + lane * 4));
;             else v[j] = *(const f32x4*)(src + j * 256 + lane * 4);
;             if (part != nullptr && isc) { const size_t po = (size_t)(row - NLAT) * DM + j * 256 + lane * 4; f32x4 ps = *(const f32x4*)(part + po);
; #pragma unroll
;                 for (int p = 1; p < 8; ++p) ps = ps + *(const f32x4*)(part + (size_t)p * (1024 * 2048) + po);
;                 v[j] = v[j] + ps * *(const f32x4*)(pgate + 4 * 12288 + j * 256 + lane * 4); }
.LBB0_1490:
	global_load_dwordx4 v[166:169], v[76:77], off offset:3072
	v_add_co_u32_e32 v152, vcc, s1, v76
	s_nop 1
	v_addc_co_u32_e32 v153, vcc, 0, v77, vcc
	global_load_dwordx4 v[170:173], v[152:153], off offset:3072
	v_add_co_u32_e32 v154, vcc, s6, v76
	s_nop 1
	v_addc_co_u32_e32 v155, vcc, 0, v77, vcc
	global_load_dwordx4 v[174:177], v[154:155], off offset:3072
	v_add_co_u32_e32 v156, vcc, s7, v76
	s_nop 1
	v_addc_co_u32_e32 v157, vcc, 0, v77, vcc
	global_load_dwordx4 v[178:181], v[156:157], off offset:3072
	v_add_co_u32_e32 v158, vcc, s10, v76
	s_nop 1
	v_addc_co_u32_e32 v159, vcc, 0, v77, vcc
	global_load_dwordx4 v[182:185], v[158:159], off offset:3072
	v_add_co_u32_e32 v160, vcc, s11, v76
	s_nop 1
	v_addc_co_u32_e32 v161, vcc, 0, v77, vcc
	global_load_dwordx4 v[186:189], v[160:161], off offset:3072
	v_add_co_u32_e32 v162, vcc, s14, v76
	s_nop 1
	v_addc_co_u32_e32 v163, vcc, 0, v77, vcc
	global_load_dwordx4 v[190:193], v[162:163], off offset:3072
	v_add_co_u32_e32 v164, vcc, s15, v76
	s_nop 1
	v_addc_co_u32_e32 v165, vcc, 0, v77, vcc
	global_load_dwordx4 v[194:197], v[164:165], off offset:3072
	s_waitcnt vmcnt(0)
	v_pk_add_f32 v[20:21], v[166:167], v[170:171]
	v_pk_add_f32 v[22:23], v[168:169], v[172:173]
	v_pk_add_f32 v[20:21], v[20:21], v[174:175]
	v_pk_add_f32 v[22:23], v[22:23], v[176:177]
	v_pk_add_f32 v[20:21], v[20:21], v[178:179]
	v_pk_add_f32 v[22:23], v[22:23], v[180:181]
	v_pk_add_f32 v[20:21], v[20:21], v[182:183]
	v_pk_add_f32 v[22:23], v[22:23], v[184:185]
	v_pk_add_f32 v[20:21], v[20:21], v[186:187]
	v_pk_add_f32 v[22:23], v[22:23], v[188:189]
	v_pk_add_f32 v[20:21], v[20:21], v[190:191]
	v_pk_add_f32 v[22:23], v[22:23], v[192:193]
	v_pk_add_f32 v[22:23], v[22:23], v[196:197]
	v_pk_add_f32 v[20:21], v[20:21], v[194:195]
	global_load_dwordx4 v[16:19], v[40:41], off offset:3072
	s_waitcnt vmcnt(0)
	v_pk_fma_f32 v[14:15], v[22:23], v[18:19], v[14:15]
	v_pk_fma_f32 v[12:13], v[20:21], v[16:17], v[12:13]
.LBB0_1491:
	s_or_b64 exec, exec, s[8:9]
	s_and_saveexec_b64 s[8:9], s[40:41]
	s_xor_b64 s[8:9], exec, s[8:9]
	s_cbranch_execz .LBB0_1512
	v_mov_b32_e32 v18, v110
	v_mov_b32_e32 v19, v111
	v_lshlrev_b32_e32 v16, 16, v18
	v_and_b32_e32 v17, 0xffff0000, v18
	v_lshlrev_b32_e32 v18, 16, v19
	v_and_b32_e32 v19, 0xffff0000, v19
	s_andn2_saveexec_b64 s[8:9], s[8:9]
	s_cbranch_execnz .LBB0_1513

; __device__ __forceinline__ void phase_norm_mod(const float* srcL, const float* srcC, const float* g, const float* mod_sh, const float* mod_sc, bf16_t* dst, int nrows, const float* part = nullptr, const float* pgate = nullptr, const bf16_t* srcLb = nullptr) {
;     ...
;             if (srcLb != nullptr && !isc) { const unsigned long long w = *(const unsigned long long*)(srcLb + (size_t)row * DM + j * 256 + lane * 4); const unsigned lo = (unsigned)w, hi = (unsigned)(w >> 32);
;                 v[j] = (f32x4){__uint_as_float(lo << 16), __uint_as_float(lo & 0xffff0000u), __uint_as_float(hi << 16), __uint_as_float(hi & 0xffff0000u)}; }
;             else if (srcLb == nullptr && !isc) v[j] = __builtin_nontemporal_load((const f32x4*)(src + j * 256 + lane * 4));
;             else v[j] = *(const f32x4*)(src + j * 256 + lane * 4);
;             if (part != nullptr && isc) { const size_t po = (size_t)(row - NLAT) * DM + j * 256 + lane * 4; f32x4 ps = *(const f32x4*)(part + po);
; #pragma unroll
;                 for (int p = 1; p < 8; ++p) ps = ps + *(const f32x4*)(part + (size_t)p * (1024 * 2048) + po);
;                 v[j] = v[j] + ps * *(const f32x4*)(pgate + 4 * 12288 + j * 256 + lane * 4); }
.LBB0_1494:
	v_add_co_u32_e32 v150, vcc, 0x1000, v76
	s_nop 1
	v_addc_co_u32_e32 v151, vcc, 0, v77, vcc
	global_load_dwordx4 v[166:169], v[150:151], off
	v_add_co_u32_e32 v152, vcc, 0x801000, v76
	s_nop 1
	v_addc_co_u32_e32 v153, vcc, 0, v77, vcc
	global_load_dwordx4 v[170:173], v[152:153], off
	v_add_co_u32_e32 v154, vcc, 0x1001000, v76
	s_nop 1
	v_addc_co_u32_e32 v155, vcc, 0, v77, vcc
	global_load_dwordx4 v[174:177], v[154:155], off
	v_add_co_u32_e32 v156, vcc, 0x1801000, v76
	s_nop 1
	v_addc_co_u32_e32 v157, vcc, 0, v77, vcc
	global_load_dwordx4 v[178:181], v[156:157], off
	v_add_co_u32_e32 v158, vcc, 0x2001000, v76
	s_nop 1
	v_addc_co_u32_e32 v159, vcc, 0, v77, vcc
	global_load_dwordx4 v[182:185], v[158:159], off
	v_add_co_u32_e32 v160, vcc, 0x2801000, v76
	s_nop 1
	v_addc_co_u32_e32 v161, vcc, 0, v77, vcc
	global_load_dwordx4 v[186:189], v[160:161], off
	v_add_co_u32_e32 v162, vcc, 0x3001000, v76
	s_nop 1
	v_addc_co_u32_e32 v163, vcc, 0, v77, vcc
	global_load_dwordx4 v[190:193], v[162:163], off
	v_add_co_u32_e32 v164, vcc, 0x3801000, v76
	s_nop 1
	v_addc_co_u32_e32 v165, vcc, 0, v77, vcc
	global_load_dwordx4 v[194:197], v[164:165], off
	s_waitcnt vmcnt(0)
	v_pk_add_f32 v[24:25], v[166:167], v[170:171]
	v_pk_add_f32 v[26:27], v[168:169], v[172:173]
	v_pk_add_f32 v[24:25], v[24:25], v[174:175]
	v_pk_add_f32 v[26:27], v[26:27], v[176:177]
	v_pk_add_f32 v[24:25], v[24:25], v[178:179]
	v_pk_add_f32 v[26:27], v[26:27], v[180:181]
	v_pk_add_f32 v[24:25], v[24:25], v[182:183]
	v_pk_add_f32 v[26:27], v[26:27], v[184:185]
	v_pk_add_f32 v[24:25], v[24:25], v[186:187]
	v_pk_add_f32 v[26:27], v[26:27], v[188:189]
	v_pk_add_f32 v[24:25], v[24:25], v[190:191]
	v_pk_add_f32 v[26:27], v[26:27], v[192:193]
	v_pk_add_f32 v[26:27], v[26:27], v[196:197]
	v_pk_add_f32 v[24:25], v[24:25], v[194:195]
	global_load_dwordx4 v[20:23], v[44:45], off
	s_waitcnt vmcnt(0)
	v_pk_fma_f32 v[18:19], v[26:27], v[22:23], v[18:19]
	v_pk_fma_f32 v[16:17], v[24:25], v[20:21], v[16:17]
.LBB0_1495:
	s_or_b64 exec, exec, s[8:9]
	s_and_saveexec_b64 s[8:9], s[40:41]
	s_xor_b64 s[8:9], exec, s[8:9]
	s_cbranch_execz .LBB0_1514
	v_mov_b32_e32 v22, v112
	v_mov_b32_e32 v23, v113
	v_lshlrev_b32_e32 v20, 16, v22
	v_and_b32_e32 v21, 0xffff0000, v22
	v_lshlrev_b32_e32 v22, 16, v23
	v_and_b32_e32 v23, 0xffff0000, v23
	s_andn2_saveexec_b64 s[8:9], s[8:9]
	s_cbranch_execnz .LBB0_1515

; __device__ __forceinline__ void phase_norm_mod(const float* srcL, const float* srcC, const float* g, const float* mod_sh, const float* mod_sc, bf16_t* dst, int nrows, const float* part = nullptr, const float* pgate = nullptr, const bf16_t* srcLb = nullptr) {
;     ...
;             if (srcLb != nullptr && !isc) { const unsigned long long w = *(const unsigned long long*)(srcLb + (size_t)row * DM + j * 256 + lane * 4); const unsigned lo = (unsigned)w, hi = (unsigned)(w >> 32);
;                 v[j] = (f32x4){__uint_as_float(lo << 16), __uint_as_float(lo & 0xffff0000u), __uint_as_float(hi << 16), __uint_as_float(hi & 0xffff0000u)}; }
;             else if (srcLb == nullptr && !isc) v[j] = __builtin_nontemporal_load((const f32x4*)(src + j * 256 + lane * 4));
;             else v[j] = *(const f32x4*)(src + j * 256 + lane * 4);
;             if (part != nullptr && isc) { const size_t po = (size_t)(row - NLAT) * DM + j * 256 + lane * 4; f32x4 ps = *(const f32x4*)(part + po);
; #pragma unroll
;                 for (int p = 1; p < 8; ++p) ps = ps + *(const f32x4*)(part + (size_t)p * (1024 * 2048) + po);
;                 v[j] = v[j] + ps * *(const f32x4*)(pgate + 4 * 12288 + j * 256 + lane * 4); }
.LBB0_1498:
	v_add_co_u32_e32 v150, vcc, 0x1000, v76
	s_nop 1
	v_addc_co_u32_e32 v151, vcc, 0, v77, vcc
	global_load_dwordx4 v[166:169], v[150:151], off offset:1024
	v_add_co_u32_e32 v152, vcc, 0x801000, v76
	s_nop 1
	v_addc_co_u32_e32 v153, vcc, 0, v77, vcc
	global_load_dwordx4 v[170:173], v[152:153], off offset:1024
	v_add_co_u32_e32 v154, vcc, 0x1001000, v76
	s_nop 1
	v_addc_co_u32_e32 v155, vcc, 0, v77, vcc
	global_load_dwordx4 v[174:177], v[154:155], off offset:1024
	v_add_co_u32_e32 v156, vcc, 0x1801000, v76
	s_nop 1
	v_addc_co_u32_e32 v157, vcc, 0, v77, vcc
	global_load_dwordx4 v[178:181], v[156:157], off offset:1024
	v_add_co_u32_e32 v158, vcc, 0x2001000, v76
	s_nop 1
	v_addc_co_u32_e32 v159, vcc, 0, v77, vcc
	global_load_dwordx4 v[182:185], v[158:159], off offset:1024
	v_add_co_u32_e32 v160, vcc, 0x2801000, v76
	s_nop 1
	v_addc_co_u32_e32 v161, vcc, 0, v77, vcc
	global_load_dwordx4 v[186:189], v[160:161], off offset:1024
	v_add_co_u32_e32 v162, vcc, 0x3001000, v76
	s_nop 1
	v_addc_co_u32_e32 v163, vcc, 0, v77, vcc
	global_load_dwordx4 v[190:193], v[162:163], off offset:1024
	v_add_co_u32_e32 v164, vcc, 0x3801000, v76
	s_nop 1
	v_addc_co_u32_e32 v165, vcc, 0, v77, vcc
	global_load_dwordx4 v[194:197], v[164:165], off offset:1024
	s_waitcnt vmcnt(0)
	v_pk_add_f32 v[28:29], v[166:167], v[170:171]
	v_pk_add_f32 v[30:31], v[168:169], v[172:173]
	v_pk_add_f32 v[28:29], v[28:29], v[174:175]
	v_pk_add_f32 v[30:31], v[30:31], v[176:177]
	v_pk_add_f32 v[28:29], v[28:29], v[178:179]
	v_pk_add_f32 v[30:31], v[30:31], v[180:181]
	v_pk_add_f32 v[28:29], v[28:29], v[182:183]
	v_pk_add_f32 v[30:31], v[30:31], v[184:185]
	v_pk_add_f32 v[28:29], v[28:29], v[186:187]
	v_pk_add_f32 v[30:31], v[30:31], v[188:189]
	v_pk_add_f32 v[28:29], v[28:29], v[190:191]
	v_pk_add_f32 v[30:31], v[30:31], v[192:193]
	v_pk_add_f32 v[30:31], v[30:31], v[196:197]
	v_pk_add_f32 v[28:29], v[28:29], v[194:195]
	global_load_dwordx4 v[24:27], v[46:47], off
	s_waitcnt vmcnt(0)
	v_pk_fma_f32 v[22:23], v[30:31], v[26:27], v[22:23]
	v_pk_fma_f32 v[20:21], v[28:29], v[24:25], v[20:21]
.LBB0_1499:
	s_or_b64 exec, exec, s[8:9]
	s_and_saveexec_b64 s[8:9], s[40:41]
	s_xor_b64 s[8:9], exec, s[8:9]
	s_cbranch_execz .LBB0_1516
	v_mov_b32_e32 v26, v114
	v_mov_b32_e32 v27, v115
	v_lshlrev_b32_e32 v24, 16, v26
	v_and_b32_e32 v25, 0xffff0000, v26
	v_lshlrev_b32_e32 v26, 16, v27
	v_and_b32_e32 v27, 0xffff0000, v27
	s_andn2_saveexec_b64 s[8:9], s[8:9]
	s_cbranch_execnz .LBB0_1517

; __device__ __forceinline__ void phase_norm_mod(const float* srcL, const float* srcC, const float* g, const float* mod_sh, const float* mod_sc, bf16_t* dst, int nrows, const float* part = nullptr, const float* pgate = nullptr, const bf16_t* srcLb = nullptr) {
;     ...
;             if (srcLb != nullptr && !isc) { const unsigned long long w = *(const unsigned long long*)(srcLb + (size_t)row * DM + j * 256 + lane * 4); const unsigned lo = (unsigned)w, hi = (unsigned)(w >> 32);
;                 v[j] = (f32x4){__uint_as_float(lo << 16), __uint_as_float(lo & 0xffff0000u), __uint_as_float(hi << 16), __uint_as_float(hi & 0xffff0000u)}; }
;             else if (srcLb == nullptr && !isc) v[j] = __builtin_nontemporal_load((const f32x4*)(src + j * 256 + lane * 4));
;             else v[j] = *(const f32x4*)(src + j * 256 + lane * 4);
;             if (part != nullptr && isc) { const size_t po = (size_t)(row - NLAT) * DM + j * 256 + lane * 4; f32x4 ps = *(const f32x4*)(part + po);
; #pragma unroll
;                 for (int p = 1; p < 8; ++p) ps = ps + *(const f32x4*)(part + (size_t)p * (1024 * 2048) + po);
;                 v[j] = v[j] + ps * *(const f32x4*)(pgate + 4 * 12288 + j * 256 + lane * 4); }
.LBB0_1502:
	v_add_co_u32_e32 v150, vcc, 0x1000, v76
	s_nop 1
	v_addc_co_u32_e32 v151, vcc, 0, v77, vcc
	global_load_dwordx4 v[166:169], v[150:151], off offset:2048
	v_add_co_u32_e32 v152, vcc, 0x801000, v76
	s_nop 1
	v_addc_co_u32_e32 v153, vcc, 0, v77, vcc
	global_load_dwordx4 v[170:173], v[152:153], off offset:2048
	v_add_co_u32_e32 v154, vcc, 0x1001000, v76
	s_nop 1
	v_addc_co_u32_e32 v155, vcc, 0, v77, vcc
	global_load_dwordx4 v[174:177], v[154:155], off offset:2048
	v_add_co_u32_e32 v156, vcc, 0x1801000, v76
	s_nop 1
	v_addc_co_u32_e32 v157, vcc, 0, v77, vcc
	global_load_dwordx4 v[178:181], v[156:157], off offset:2048
	v_add_co_u32_e32 v158, vcc, 0x2001000, v76
	s_nop 1
	v_addc_co_u32_e32 v159, vcc, 0, v77, vcc
	global_load_dwordx4 v[182:185], v[158:159], off offset:2048
	v_add_co_u32_e32 v160, vcc, 0x2801000, v76
	s_nop 1
	v_addc_co_u32_e32 v161, vcc, 0, v77, vcc
	global_load_dwordx4 v[186:189], v[160:161], off offset:2048
	v_add_co_u32_e32 v162, vcc, 0x3001000, v76
	s_nop 1
	v_addc_co_u32_e32 v163, vcc, 0, v77, vcc
	global_load_dwordx4 v[190:193], v[162:163], off offset:2048
	v_add_co_u32_e32 v164, vcc, 0x3801000, v76
	s_nop 1
	v_addc_co_u32_e32 v165, vcc, 0, v77, vcc
	global_load_dwordx4 v[194:197], v[164:165], off offset:2048
	s_waitcnt vmcnt(0)
	v_pk_add_f32 v[90:91], v[166:167], v[170:171]
	v_pk_add_f32 v[82:83], v[168:169], v[172:173]
	v_pk_add_f32 v[90:91], v[90:91], v[174:175]
	v_pk_add_f32 v[82:83], v[82:83], v[176:177]
	v_pk_add_f32 v[90:91], v[90:91], v[178:179]
	v_pk_add_f32 v[82:83], v[82:83], v[180:181]
	v_pk_add_f32 v[90:91], v[90:91], v[182:183]
	v_pk_add_f32 v[82:83], v[82:83], v[184:185]
	v_pk_add_f32 v[90:91], v[90:91], v[186:187]
	v_pk_add_f32 v[82:83], v[82:83], v[188:189]
	v_pk_add_f32 v[90:91], v[90:91], v[190:191]
	v_pk_add_f32 v[82:83], v[82:83], v[192:193]
	v_pk_add_f32 v[82:83], v[82:83], v[196:197]
	v_pk_add_f32 v[90:91], v[90:91], v[194:195]
	global_load_dwordx4 v[28:31], v[48:49], off
	s_waitcnt vmcnt(0)
	v_pk_fma_f32 v[26:27], v[82:83], v[30:31], v[26:27]
	v_pk_fma_f32 v[24:25], v[90:91], v[28:29], v[24:25]
.LBB0_1503:
	s_or_b64 exec, exec, s[8:9]
	s_and_saveexec_b64 s[8:9], s[40:41]
	s_xor_b64 s[8:9], exec, s[8:9]
	s_cbranch_execz .LBB0_1518
	v_mov_b32_e32 v30, v116
	v_mov_b32_e32 v31, v117
	v_lshlrev_b32_e32 v28, 16, v30
	v_and_b32_e32 v29, 0xffff0000, v30
	v_lshlrev_b32_e32 v30, 16, v31
	v_and_b32_e32 v31, 0xffff0000, v31
	s_andn2_saveexec_b64 s[8:9], s[8:9]
	s_cbranch_execnz .LBB0_1519
